# half-tile stagger between CU partner blocks in the w_br and w_out GEMM phases
# baseline (speedup 1.0000x reference)
.LBB0_698:
	s_or_b64 exec, exec, s[0:1]
	v_readlane_b32 s0, v246, 26
	v_readlane_b32 s1, v246, 27
	s_andn2_b64 vcc, exec, s[0:1]
	s_waitcnt lgkmcnt(0)
	v_cndmask_b32_e64 v0, 0, 1, s[0:1]
	v_cmp_ne_u32_e64 s[6:7], 1, v0
	s_barrier
	s_cbranch_vccnz .LBB0_700
	s_sleep 127
	s_sleep 127
	s_sleep 106

.LBB0_763:
	s_or_b64 exec, exec, s[2:3]
	s_and_b64 vcc, exec, s[6:7]
	s_waitcnt lgkmcnt(0)
	s_barrier
	s_cbranch_vccnz .LBB0_765
	s_sleep 127
	s_sleep 127
	s_sleep 43
